# v22 + P10 epilogue: cs/bw loads batched (4 serialized round trips -> 2)
# speedup vs baseline: 1.0120x; 1.0019x over previous
;     __device__ __forceinline__ void operator()(f32x4 (&acc)[2][2][4][2], const Unit& u, int wr, int wc, int fr, int fq) const {
;         const int chb = (u.ocol >> 1) + wc * 32 + 8 * fq;
;         {
;             const int colq = u.ocol + wc * 32 + 8 * fq;
;             float nmv[2][4], rsv[2][4];
; #pragma unroll
;             for (int ai = 0; ai < 2; ++ai)
; #pragma unroll
;                 for (int m = 0; m < 4; ++m) { const f32x2 st = *(const f32x2*)(ps + (size_t)(u.orow + ai * HALF + wr * 64 + m * 16 + fr) * 2); rsv[ai][m] = st[1]; nmv[ai][m] = -st[0] * st[1]; }
; #pragma unroll
;             for (int bj = 0; bj < 2; ++bj)
; #pragma unroll
;                 for (int n = 0; n < 2; ++n) { f32x4 cv = *(const f32x4*)(cs + colq + bj * HALF + 4 * n), bv = *(const f32x4*)(bw + colq + bj * HALF + 4 * n);
;                     asm volatile("" : "+v"(cv), "+v"(bv));
; #pragma unroll
;                     for (int ai = 0; ai < 2; ++ai)
; #pragma unroll
;                         for (int m = 0; m < 4; ++m) acc[ai][bj][m][n] = acc[ai][bj][m][n] * rsv[ai][m] + (cv * nmv[ai][m] + bv); }
;         }
; #pragma unroll
;         for (int ai = 0; ai < 2; ++ai) { const int run = (u.orow + ai * HALF + wr * 64) >> 6;
; #pragma unroll
;             for (int bj = 0; bj < 2; ++bj)
; #pragma unroll
;                 for (int n = 0; n < 2; ++n) {
;                     if (fr < 2) *(f32x4*)(rawH + ((size_t)(run * 2 + fr) * 2 + bj) * DFF + chb + 4 * n) = acc[ai][bj][0][n];
.LBB0_980:
	s_add_i32 s1, s1, s66
	v_add_u32_e32 v212, s1, v232
	v_readlane_b32 s2, v255, 4
	v_ashrrev_i32_e32 v213, 31, v212
	v_readlane_b32 s3, v255, 5
	v_add_u32_e32 v210, 16, v212
	v_ashrrev_i32_e32 v211, 31, v210
	v_lshl_add_u64 v[130:131], v[212:213], 3, s[2:3]
	v_add_u32_e32 v208, 32, v212
	global_load_dwordx2 v[156:157], v[130:131], off
	v_lshl_add_u64 v[130:131], v[210:211], 3, s[2:3]
	v_ashrrev_i32_e32 v209, 31, v208
	v_add_u32_e32 v206, 48, v212
	global_load_dwordx2 v[216:217], v[130:131], off
	v_lshl_add_u64 v[130:131], v[208:209], 3, s[2:3]
	v_ashrrev_i32_e32 v207, 31, v206
	v_add_u32_e32 v204, 0x80, v212
	global_load_dwordx2 v[218:219], v[130:131], off
	v_lshl_add_u64 v[130:131], v[206:207], 3, s[2:3]
	v_ashrrev_i32_e32 v205, 31, v204
	v_add_u32_e32 v202, 0x90, v212
	global_load_dwordx2 v[154:155], v[130:131], off
	v_lshl_add_u64 v[130:131], v[204:205], 3, s[2:3]
	v_ashrrev_i32_e32 v203, 31, v202
	v_add_u32_e32 v200, 0xa0, v212
	global_load_dwordx2 v[152:153], v[130:131], off
	v_lshl_add_u64 v[130:131], v[202:203], 3, s[2:3]
	v_ashrrev_i32_e32 v201, 31, v200
	v_add_u32_e32 v198, 0xb0, v212
	global_load_dwordx2 v[220:221], v[130:131], off
	v_lshl_add_u64 v[130:131], v[200:201], 3, s[2:3]
	v_ashrrev_i32_e32 v199, 31, v198
	global_load_dwordx2 v[222:223], v[130:131], off
	v_lshl_add_u64 v[130:131], v[198:199], 3, s[2:3]
	global_load_dwordx2 v[150:151], v[130:131], off
	v_add_u32_e32 v130, s0, v233
	v_ashrrev_i32_e32 v131, 31, v130
	v_readlane_b32 s6, v251, 41
	v_lshlrev_b64 v[130:131], 2, v[130:131]
	v_readlane_b32 s7, v251, 42
	s_ashr_i32 s2, s0, 1
	s_ashr_i32 s0, s1, 5
	v_lshl_add_u64 v[142:143], s[6:7], 0, v[130:131]
	v_readlane_b32 s6, v251, 43
	v_readlane_b32 s7, v251, 44
	s_and_b32 s0, s0, -2
	s_mov_b32 s8, 0xb000
	v_lshl_add_u64 v[144:145], s[6:7], 0, v[130:131]
	global_load_dwordx4 v[130:133], v[144:145], off
	global_load_dwordx4 v[138:141], v[142:143], off
	global_load_dwordx4 v[170:173], v[144:145], off offset:16
	global_load_dwordx4 v[174:177], v[142:143], off offset:16
	global_load_dwordx4 v[166:169], v[142:143], off offset:512
	global_load_dwordx4 v[158:161], v[144:145], off offset:528
	global_load_dwordx4 v[162:165], v[142:143], off offset:528
	v_add_u32_e32 v214, s2, v233
	v_ashrrev_i32_e32 v215, 31, v214
	s_waitcnt vmcnt(0)
	v_mul_f32_e64 v224, v157, -v156
	v_pk_fma_f32 v[136:137], v[224:225], v[140:141], v[132:133] op_sel_hi:[0,1,1]
	v_pk_fma_f32 v[134:135], v[224:225], v[138:139], v[130:131] op_sel_hi:[0,1,1]
	v_pk_fma_f32 v[134:135], v[126:127], v[156:157], v[134:135] op_sel:[0,1,0]
	v_pk_fma_f32 v[136:137], v[128:129], v[156:157], v[136:137] op_sel:[0,1,0]
	global_load_dwordx4 v[126:129], v[144:145], off offset:512
	v_add_u32_e32 v142, s0, v232
	v_mad_i64_i32 v[228:229], s[2:3], v142, s8, 0
	v_lshl_add_u64 v[142:143], s[78:79], 0, v[228:229]
	v_lshl_add_u64 v[142:143], v[214:215], 2, v[142:143]
	s_waitcnt vmcnt(0)
	s_and_saveexec_b64 s[2:3], s[40:41]
	s_cbranch_execz .LBB0_982
	global_store_dwordx4 v[142:143], v[134:137], off
